# k31_pksplit
# speedup vs baseline: 1.0019x; 1.0019x over previous
; DI int crow(int i, int h) { return (i & 3) + 8 * (i >> 2) + 4 * h; }
; DI void phase_gla_scan(const Params& p, char* smem) {
;     ...
;   for (int n = 0; n < NCH; ++n) {
;     const int t0 = n * 64;
;     ...
; #pragma unroll
;       for (int i = 0; i < 16; ++i) S[i] = dec[32 * wave + crow(i, h)] * (S[i] + acc2[i]);
.LBB0_579:
	s_or_b64 exec, exec, s[74:75]
	s_nop 8
	v_add_f32_e32 v14, v112, v14
	v_add_f32_e32 v15, v113, v15
	v_add_f32_e32 v12, v110, v12
	v_add_f32_e32 v13, v111, v13
	v_add_f32_e32 v10, v108, v10
	v_add_f32_e32 v11, v109, v11
	v_add_f32_e32 v8, v106, v8
	v_add_f32_e32 v9, v107, v9
	v_add_f32_e32 v6, v104, v6
	v_add_f32_e32 v7, v105, v7
	v_add_f32_e32 v4, v102, v4
	v_add_f32_e32 v5, v103, v5
	v_add_f32_e32 v2, v100, v2
	v_add_f32_e32 v3, v101, v3
	v_add_f32_e32 v0, v98, v0
	v_add_f32_e32 v1, v99, v1
	s_add_i32 s80, s80, 0x20000
	s_add_i32 s71, s71, 0x60800
	s_add_i32 s3, s3, 64
	v_mul_f32_e32 v98, v82, v0
	v_mul_f32_e32 v99, v83, v1
	v_mul_f32_e32 v100, v2, v84
	v_mul_f32_e32 v101, v3, v85
	v_mul_f32_e32 v102, v4, v78
	v_mul_f32_e32 v103, v5, v79
	v_mul_f32_e32 v104, v6, v80
	v_mul_f32_e32 v105, v7, v81
	v_mul_f32_e32 v106, v8, v74
	v_mul_f32_e32 v107, v9, v75
	v_mul_f32_e32 v108, v10, v76
	v_mul_f32_e32 v109, v11, v77
	v_mul_f32_e32 v110, v12, v70
	v_mul_f32_e32 v111, v13, v71
	v_mul_f32_e32 v112, v14, v72
	v_mul_f32_e32 v113, v15, v73
	s_cmp_lg_u32 s80, 0x1020000
	v_add_u32_e32 v88, 0x800, v88
	s_cbranch_scc0 .LBB0_617
